# attention: remaining xor-32 lane exchanges (Q head-norm, softmax denominator) via v_permlane32_swap instead of ds_bpermute
# baseline (speedup 1.0000x reference)
.LBB0_1166:
	v_readlane_b32 s12, v243, 21
	v_readlane_b32 s13, v243, 22
	v_readlane_b32 s16, v243, 25
	v_readlane_b32 s17, v243, 26
	v_readlane_b32 s20, v243, 29
	v_readlane_b32 s21, v243, 30
	v_ashrrev_i32_e32 v165, 31, v164
	s_mov_b64 s[12:13], s[16:17]
	s_mov_b64 s[16:17], s[20:21]
	v_lshl_add_u64 v[80:81], v[164:165], 2, s[16:17]
	v_mov_b32_e32 v80, v240
	v_mov_b32_e32 v254, v188
	v_mov_b32_e32 v255, v188
	s_nop 1
	v_permlane32_swap_b32_e32 v254, v255
	v_readlane_b32 s11, v243, 60
	v_readlane_b32 s6, v243, 50
	v_readlane_b32 s7, v243, 51
	v_readlane_b32 s14, v243, 23
	s_waitcnt lgkmcnt(0)
	v_add_f32_e32 v82, v254, v255
	v_readlane_b32 s15, v243, 24
	v_readlane_b32 s18, v243, 27
	v_readlane_b32 s19, v243, 28
	v_readlane_b32 s22, v243, 31
	v_readlane_b32 s23, v243, 32
	v_readlane_b32 s24, v243, 33
	v_readlane_b32 s25, v243, 34
	v_readlane_b32 s26, v243, 35
	v_readlane_b32 s27, v243, 36
	s_waitcnt vmcnt(0)
	v_fmamk_f32 v80, v80, 0x3fb8aa3b, v0
	v_exp_f32_e32 v83, v80
	v_lshl_add_u64 v[80:81], v[162:163], 1, v[154:155]
	v_add_f32_e32 v82, v83, v82
	v_div_scale_f32 v84, s[0:1], v82, v82, 1.0
	v_rcp_f32_e32 v85, v84
	s_nop 0
	v_fma_f32 v86, -v84, v85, 1.0
	v_fmac_f32_e32 v85, v86, v85
	v_div_scale_f32 v86, vcc, 1.0, v82, 1.0
	v_mul_f32_e32 v87, v86, v85
	v_fma_f32 v88, -v84, v87, v86
	v_fmac_f32_e32 v87, v88, v85
	v_fma_f32 v84, -v84, v87, v86
	v_div_fmas_f32 v84, v84, v85, v87
	v_div_fixup_f32 v82, v84, v82, 1.0
	v_lshlrev_b64 v[84:85], 11, v[160:161]
	v_lshl_add_u64 v[84:85], v[80:81], 0, v[84:85]
	v_and_b32_e32 v252, 32, v168
	v_lshrrev_b32_e32 v252, 2, v252
	v_mov_b32_e32 v253, 0
	v_lshl_add_u64 v[84:85], v[84:85], 0, v[252:253]
	v_pk_mul_f32 v[48:49], v[48:49], v[82:83] op_sel_hi:[1,0]
	v_pk_mul_f32 v[50:51], v[50:51], v[82:83] op_sel_hi:[1,0]
	v_pk_mul_f32 v[52:53], v[52:53], v[82:83] op_sel_hi:[1,0]
	v_pk_mul_f32 v[54:55], v[54:55], v[82:83] op_sel_hi:[1,0]
	v_cvt_pk_bf16_f32 v244, v48, v49
	v_cvt_pk_bf16_f32 v245, v50, v51
	v_cvt_pk_bf16_f32 v246, v52, v53
	v_cvt_pk_bf16_f32 v247, v54, v55
	s_nop 1
	v_permlane32_swap_b32_e32 v244, v246
	v_permlane32_swap_b32_e32 v245, v247
	global_store_dwordx4 v[84:85], v[244:247], off offset:64
	v_pk_mul_f32 v[56:57], v[56:57], v[82:83] op_sel_hi:[1,0]
	v_pk_mul_f32 v[58:59], v[58:59], v[82:83] op_sel_hi:[1,0]
	v_pk_mul_f32 v[60:61], v[60:61], v[82:83] op_sel_hi:[1,0]
	v_pk_mul_f32 v[62:63], v[62:63], v[82:83] op_sel_hi:[1,0]
	v_cvt_pk_bf16_f32 v248, v56, v57
	v_cvt_pk_bf16_f32 v249, v58, v59
	v_cvt_pk_bf16_f32 v250, v60, v61
	v_cvt_pk_bf16_f32 v251, v62, v63
	s_nop 1
	v_permlane32_swap_b32_e32 v248, v250
	v_permlane32_swap_b32_e32 v249, v251
	global_store_dwordx4 v[84:85], v[248:251], off offset:96
	ds_bpermute_b32 v48, v202, v187
	v_pk_mul_f32 v[64:65], v[64:65], v[82:83] op_sel_hi:[1,0]
	v_pk_mul_f32 v[66:67], v[66:67], v[82:83] op_sel_hi:[1,0]
	v_pk_mul_f32 v[68:69], v[68:69], v[82:83] op_sel_hi:[1,0]
	v_pk_mul_f32 v[70:71], v[70:71], v[82:83] op_sel_hi:[1,0]
	v_cvt_pk_bf16_f32 v244, v64, v65
	v_cvt_pk_bf16_f32 v245, v66, v67
	v_cvt_pk_bf16_f32 v246, v68, v69
	v_cvt_pk_bf16_f32 v247, v70, v71
	s_nop 1
	v_permlane32_swap_b32_e32 v244, v246
	v_permlane32_swap_b32_e32 v245, v247
	global_store_dwordx4 v[84:85], v[244:247], off
	v_pk_mul_f32 v[72:73], v[72:73], v[82:83] op_sel_hi:[1,0]
	v_pk_mul_f32 v[74:75], v[74:75], v[82:83] op_sel_hi:[1,0]
	v_pk_mul_f32 v[76:77], v[76:77], v[82:83] op_sel_hi:[1,0]
	v_pk_mul_f32 v[78:79], v[78:79], v[82:83] op_sel_hi:[1,0]
	v_cvt_pk_bf16_f32 v248, v72, v73
	v_cvt_pk_bf16_f32 v249, v74, v75
	v_cvt_pk_bf16_f32 v250, v76, v77
	v_cvt_pk_bf16_f32 v251, v78, v79
	s_nop 1
	v_permlane32_swap_b32_e32 v248, v250
	v_permlane32_swap_b32_e32 v249, v251
	global_store_dwordx4 v[84:85], v[248:251], off offset:32
	s_waitcnt lgkmcnt(0)
	v_add_f32_e32 v48, v187, v48
	v_add_f32_e32 v48, v83, v48
	v_div_scale_f32 v49, s[0:1], v48, v48, 1.0
	v_rcp_f32_e32 v50, v49
	s_nop 0
	v_fma_f32 v51, -v49, v50, 1.0
	v_fmac_f32_e32 v50, v51, v50
	v_div_scale_f32 v51, vcc, 1.0, v48, 1.0
	v_mul_f32_e32 v52, v51, v50
	v_fma_f32 v53, -v49, v52, v51
	v_fmac_f32_e32 v52, v53, v50
	v_fma_f32 v49, -v49, v52, v51
	v_div_fmas_f32 v49, v49, v50, v52
	v_div_fixup_f32 v48, v49, v48, 1.0
	v_lshlrev_b64 v[50:51], 11, v[166:167]
	v_lshl_add_u64 v[50:51], v[80:81], 0, v[50:51]
	v_lshl_add_u64 v[50:51], v[50:51], 0, v[252:253]
	v_pk_mul_f32 v[32:33], v[32:33], v[48:49] op_sel_hi:[1,0]
	v_pk_mul_f32 v[34:35], v[34:35], v[48:49] op_sel_hi:[1,0]
	v_pk_mul_f32 v[36:37], v[36:37], v[48:49] op_sel_hi:[1,0]
	v_pk_mul_f32 v[38:39], v[38:39], v[48:49] op_sel_hi:[1,0]
	v_cvt_pk_bf16_f32 v244, v32, v33
	v_cvt_pk_bf16_f32 v245, v34, v35
	v_cvt_pk_bf16_f32 v246, v36, v37
	v_cvt_pk_bf16_f32 v247, v38, v39
	s_nop 1
	v_permlane32_swap_b32_e32 v244, v246
	v_permlane32_swap_b32_e32 v245, v247
	global_store_dwordx4 v[50:51], v[244:247], off
	v_pk_mul_f32 v[40:41], v[40:41], v[48:49] op_sel_hi:[1,0]
	v_pk_mul_f32 v[42:43], v[42:43], v[48:49] op_sel_hi:[1,0]
	v_pk_mul_f32 v[44:45], v[44:45], v[48:49] op_sel_hi:[1,0]
	v_pk_mul_f32 v[46:47], v[46:47], v[48:49] op_sel_hi:[1,0]
	v_cvt_pk_bf16_f32 v248, v40, v41
	v_cvt_pk_bf16_f32 v249, v42, v43
	v_cvt_pk_bf16_f32 v250, v44, v45
	v_cvt_pk_bf16_f32 v251, v46, v47
	s_nop 1
	v_permlane32_swap_b32_e32 v248, v250
	v_permlane32_swap_b32_e32 v249, v251
	global_store_dwordx4 v[50:51], v[248:251], off offset:32
	v_pk_mul_f32 v[16:17], v[16:17], v[48:49] op_sel_hi:[1,0]
	v_pk_mul_f32 v[18:19], v[18:19], v[48:49] op_sel_hi:[1,0]
	v_pk_mul_f32 v[20:21], v[20:21], v[48:49] op_sel_hi:[1,0]
	v_pk_mul_f32 v[22:23], v[22:23], v[48:49] op_sel_hi:[1,0]
	v_cvt_pk_bf16_f32 v244, v16, v17
	v_cvt_pk_bf16_f32 v245, v18, v19
	v_cvt_pk_bf16_f32 v246, v20, v21
	v_cvt_pk_bf16_f32 v247, v22, v23
	s_nop 1
	v_permlane32_swap_b32_e32 v244, v246
	v_permlane32_swap_b32_e32 v245, v247
	global_store_dwordx4 v[50:51], v[244:247], off offset:64
	v_pk_mul_f32 v[24:25], v[24:25], v[48:49] op_sel_hi:[1,0]
	v_pk_mul_f32 v[26:27], v[26:27], v[48:49] op_sel_hi:[1,0]
	v_pk_mul_f32 v[28:29], v[28:29], v[48:49] op_sel_hi:[1,0]
	v_pk_mul_f32 v[30:31], v[30:31], v[48:49] op_sel_hi:[1,0]
	v_cvt_pk_bf16_f32 v248, v24, v25
	v_cvt_pk_bf16_f32 v249, v26, v27
	v_cvt_pk_bf16_f32 v250, v28, v29
	v_cvt_pk_bf16_f32 v251, v30, v31
	s_nop 1
	v_permlane32_swap_b32_e32 v248, v250
	v_permlane32_swap_b32_e32 v249, v251
	global_store_dwordx4 v[50:51], v[248:251], off offset:96
	v_readlane_b32 s0, v243, 1
	v_readlane_b32 s2, v243, 3
	s_nop 3
	s_add_i32 s11, s11, s2
	s_cmpk_gt_i32 s11, 0x7ff
	v_readlane_b32 s1, v243, 2
	v_readlane_b32 s3, v243, 4
	s_cbranch_scc1 .LBB0_1202
.LBB0_1167:
	s_bfe_u32 s70, s11, 0x20006
	s_lshl_b32 s71, s11, 7
	s_and_b32 s71, s71, 0x1f80
	s_lshl_b32 s72, s11, 5
	s_and_b32 s72, s72, 0xffffe000
	v_readlane_b32 s74, v243, 56
	v_readlane_b32 s75, v243, 57
	s_cmp_eq_u32 s71, 0
	s_cselect_b32 s73, 0, 0xffffff80
	s_or_b32 s72, s72, s71
	s_add_i32 s72, s72, s73
	s_lshl_b32 s70, s70, 7
	s_mov_b32 s71, 0
	s_movk_i32 s78, 0xc00
	v_add_u32_e32 v220, s72, v177
	v_mov_b64_e32 v[222:223], s[74:75]
	s_nop 0
	v_mad_i64_i32 v[220:221], s[76:77], v220, s78, v[222:223]
	v_lshl_add_u64 v[220:221], v[220:221], 0, s[70:71]
	v_lshl_add_u64 v[220:221], v[220:221], 0, v[144:145]
	global_load_dwordx4 v[204:207], v[220:221], off offset:2064
	global_load_dwordx4 v[208:211], v[220:221], off offset:2048
	global_load_dwordx4 v[212:215], v[220:221], off offset:2560
	global_load_dwordx4 v[216:219], v[220:221], off offset:2576
	s_bfe_u32 s1, s11, 0x20006
	s_lshl_b32 s0, s11, 7
	v_lshl_add_u32 v164, s1, 2, v175
	v_readlane_b32 s76, v243, 29
	v_readlane_b32 s77, v243, 30
	v_mov_b32_e32 v240, v164
	v_ashrrev_i32_e32 v241, 31, v164
	s_nop 1
	v_lshl_add_u64 v[240:241], v[240:241], 2, s[76:77]
	global_load_dword v240, v[240:241], off
	s_and_b32 s0, s0, 0x1f80
	s_lshl_b32 s2, s11, 5
	v_lshlrev_b32_e32 v162, 6, v164
	v_or_b32_e32 v18, s0, v176
	s_and_b32 s2, s2, 0xffffe000
	v_ashrrev_i32_e32 v163, 31, v162
	v_lshl_add_u64 v[64:65], v[162:163], 1, v[146:147]
	v_or3_b32 v160, s2, v149, v18
	s_movk_i32 s10, 0xc00
	v_mov_b32_e32 v16, v174
	v_lshrrev_b32_e32 v48, 6, v18
	v_mad_i64_i32 v[18:19], s[4:5], v160, s10, v[64:65]
	global_load_dwordx4 v[84:87], v[18:19], off
	global_load_dwordx4 v[88:91], v[18:19], off offset:32
	global_load_dwordx4 v[94:97], v[18:19], off offset:64
	global_load_dwordx4 v[98:101], v[18:19], off offset:96
	s_mov_b32 s98, 0x18000
	s_mov_b32 s99, 0
	v_lshl_add_u64 v[244:245], v[18:19], 0, s[98:99]
	global_load_dwordx4 v[224:227], v[244:245], off
	global_load_dwordx4 v[228:231], v[244:245], off offset:32
	global_load_dwordx4 v[232:235], v[244:245], off offset:64
	global_load_dwordx4 v[236:239], v[244:245], off offset:96
	v_lshlrev_b32_e32 v60, 3, v16
	v_ashrrev_i32_e32 v61, 31, v60
	v_lshl_add_u64 v[16:17], v[60:61], 2, s[12:13]
	global_load_dwordx4 v[44:47], v[16:17], off
	global_load_dwordx4 v[40:43], v[16:17], off offset:16
	global_load_dwordx4 v[36:39], v[16:17], off offset:64
	global_load_dwordx4 v[32:35], v[16:17], off offset:80
	v_cvt_f32_i32_e32 v18, v60
	v_or_b32_e32 v51, 2, v60
	v_cvt_f32_i32_e32 v51, v51
	v_cvt_f32_ubyte0_e32 v61, v48
	v_mul_f32_e32 v18, 0xbf549a78, v18
	v_exp_f32_e32 v49, v18
	global_load_dwordx4 v[28:31], v[16:17], off offset:128
	global_load_dwordx4 v[24:27], v[16:17], off offset:144
	global_load_dwordx4 v[20:23], v[16:17], off offset:192
	s_nop 0
	global_load_dwordx4 v[16:19], v[16:17], off offset:208
	v_mul_f32_e32 v51, 0xbf549a78, v51
	v_exp_f32_e32 v53, v51
	v_mul_f32_e32 v165, 0.15915494, v49
	v_or_b32_e32 v49, 1, v60
	v_cvt_f32_i32_e32 v49, v49
	v_or_b32_e32 v57, 5, v60
	v_cvt_f32_i32_e32 v57, v57
	v_mul_f32_e32 v171, 0.15915494, v53
	v_mul_f32_e32 v49, 0xbf549a78, v49
	v_exp_f32_e32 v49, v49
	v_mul_f32_e32 v53, v171, v61
	v_mul_f32_e32 v57, 0xbf549a78, v57
	v_or_b32_e32 v59, 6, v60
	v_mul_f32_e32 v170, 0.15915494, v49
	v_mul_f32_e32 v52, v170, v61
	v_cos_f32_e32 v49, v52
	v_sin_f32_e32 v51, v52
	v_or_b32_e32 v52, 3, v60
	v_cvt_f32_i32_e32 v54, v52
	v_cos_f32_e32 v52, v53
	v_exp_f32_e32 v57, v57
	v_cvt_f32_i32_e32 v59, v59
	v_mul_f32_e32 v54, 0xbf549a78, v54
	v_exp_f32_e32 v55, v54
	v_sin_f32_e32 v54, v53
	v_or_b32_e32 v53, 4, v60
	v_cvt_f32_i32_e32 v56, v53
	v_mul_f32_e32 v187, 0.15915494, v57
	v_mul_f32_e32 v57, 0xbf549a78, v59
	v_exp_f32_e32 v63, v57
	v_mul_f32_e32 v56, 0xbf549a78, v56
	v_exp_f32_e32 v56, v56
	v_or_b32_e32 v57, 7, v60
	v_cvt_f32_i32_e32 v60, v57
	v_mul_f32_e32 v50, v165, v61
	v_mul_f32_e32 v172, 0.15915494, v55
	v_cos_f32_e32 v48, v50
	v_sin_f32_e32 v50, v50
	v_mul_f32_e32 v55, v172, v61
	v_mul_f32_e32 v173, 0.15915494, v56
	v_cos_f32_e32 v53, v55
	v_sin_f32_e32 v55, v55
	v_mul_f32_e32 v58, v173, v61
	v_mul_f32_e32 v62, v187, v61
	v_cos_f32_e32 v56, v58
	v_sin_f32_e32 v58, v58
	v_cos_f32_e32 v57, v62
	v_sin_f32_e32 v59, v62
	v_mul_f32_e32 v60, 0xbf549a78, v60
	v_mul_f32_e32 v92, 0.15915494, v63
	v_exp_f32_e32 v63, v60
	v_or_b32_e32 v166, 32, v160
	v_mad_i64_i32 v[64:65], s[4:5], v166, s10, v[64:65]
	v_mul_f32_e32 v93, 0.15915494, v63
	v_mul_f32_e32 v62, v92, v61
	v_mul_f32_e32 v63, v93, v61
	v_cos_f32_e32 v60, v62
	v_cos_f32_e32 v61, v63
	v_sin_f32_e32 v62, v62
	v_sin_f32_e32 v63, v63
	v_mul_f32_e32 v67, v165, v181
	v_mul_f32_e32 v68, v170, v181
	v_cos_f32_e32 v66, v67
	v_sin_f32_e32 v70, v67
	s_waitcnt vmcnt(15)
	v_lshlrev_b32_e32 v140, 16, v84
	v_and_b32_e32 v141, 0xffff0000, v84
	v_lshlrev_b32_e32 v132, 16, v85
	v_and_b32_e32 v133, 0xffff0000, v85
	v_pk_mul_f32 v[84:85], v[140:141], v[140:141]
	v_pk_mul_f32 v[134:135], v[132:133], v[132:133]
	v_add_f32_e32 v84, v84, v85
	v_lshlrev_b32_e32 v128, 16, v86
	v_and_b32_e32 v129, 0xffff0000, v86
	v_add_f32_e32 v84, v134, v84
	v_lshlrev_b32_e32 v120, 16, v87
	v_and_b32_e32 v121, 0xffff0000, v87
	v_pk_mul_f32 v[86:87], v[128:129], v[128:129]
	v_add_f32_e32 v84, v135, v84
	v_add_f32_e32 v84, v86, v84
	v_pk_mul_f32 v[122:123], v[120:121], v[120:121]
	v_add_f32_e32 v84, v87, v84
	s_waitcnt vmcnt(14)
	v_lshlrev_b32_e32 v142, 16, v88
	v_and_b32_e32 v143, 0xffff0000, v88
	v_add_f32_e32 v84, v122, v84
	v_lshlrev_b32_e32 v136, 16, v89
	v_and_b32_e32 v137, 0xffff0000, v89
	v_pk_mul_f32 v[88:89], v[142:143], v[142:143]
	v_add_f32_e32 v84, v123, v84
	v_add_f32_e32 v84, v88, v84
	v_pk_mul_f32 v[138:139], v[136:137], v[136:137]
	v_add_f32_e32 v84, v89, v84
	v_lshlrev_b32_e32 v130, 16, v90
	v_and_b32_e32 v131, 0xffff0000, v90
	v_add_f32_e32 v84, v138, v84
	v_lshlrev_b32_e32 v124, 16, v91
	v_and_b32_e32 v125, 0xffff0000, v91
	v_pk_mul_f32 v[90:91], v[130:131], v[130:131]
	v_add_f32_e32 v84, v139, v84
	v_add_f32_e32 v84, v90, v84
	v_pk_mul_f32 v[126:127], v[124:125], v[124:125]
	v_add_f32_e32 v84, v91, v84
	s_waitcnt vmcnt(13)
	v_lshlrev_b32_e32 v114, 16, v94
	v_and_b32_e32 v115, 0xffff0000, v94
	v_add_f32_e32 v84, v126, v84
	v_lshlrev_b32_e32 v108, 16, v95
	v_and_b32_e32 v109, 0xffff0000, v95
	v_pk_mul_f32 v[94:95], v[114:115], v[114:115]
	v_add_f32_e32 v84, v127, v84
	v_add_f32_e32 v84, v94, v84
	v_pk_mul_f32 v[110:111], v[108:109], v[108:109]
	v_add_f32_e32 v84, v95, v84
	v_lshlrev_b32_e32 v106, 16, v96
	v_and_b32_e32 v107, 0xffff0000, v96
	v_add_f32_e32 v84, v110, v84
	v_lshlrev_b32_e32 v80, 16, v97
	v_and_b32_e32 v81, 0xffff0000, v97
	v_pk_mul_f32 v[96:97], v[106:107], v[106:107]
	v_add_f32_e32 v84, v111, v84
	v_add_f32_e32 v84, v96, v84
	v_pk_mul_f32 v[102:103], v[80:81], v[80:81]
	v_add_f32_e32 v84, v97, v84
	s_waitcnt vmcnt(12)
	v_lshlrev_b32_e32 v118, 16, v98
	v_and_b32_e32 v119, 0xffff0000, v98
	v_add_f32_e32 v84, v102, v84
	v_lshlrev_b32_e32 v116, 16, v99
	v_and_b32_e32 v117, 0xffff0000, v99
	v_pk_mul_f32 v[98:99], v[118:119], v[118:119]
	v_add_f32_e32 v84, v103, v84
	v_add_f32_e32 v84, v98, v84
	v_pk_mul_f32 v[112:113], v[116:117], v[116:117]
	v_add_f32_e32 v84, v99, v84
	v_lshlrev_b32_e32 v82, 16, v100
	v_and_b32_e32 v83, 0xffff0000, v100
	v_add_f32_e32 v84, v112, v84
	v_lshlrev_b32_e32 v78, 16, v101
	v_and_b32_e32 v79, 0xffff0000, v101
	v_pk_mul_f32 v[100:101], v[82:83], v[82:83]
	v_add_f32_e32 v84, v113, v84
	v_add_f32_e32 v84, v100, v84
	v_pk_mul_f32 v[104:105], v[78:79], v[78:79]
	v_add_f32_e32 v84, v101, v84
	v_add_f32_e32 v84, v104, v84
	v_add_f32_e32 v85, v105, v84
	v_mov_b32_e32 v254, v85
	v_mov_b32_e32 v255, v85
	s_nop 1
	v_permlane32_swap_b32_e32 v254, v255
	v_cos_f32_e32 v67, v68
	v_sin_f32_e32 v71, v68
	v_mul_f32_e32 v69, v171, v181
	v_mul_f32_e32 v72, v172, v181
	s_waitcnt lgkmcnt(0)
	v_add_f32_e32 v85, v254, v255
	v_fmamk_f32 v85, v85, 0x3c800000, v186
	v_rsq_f32_e32 v88, v85
	v_cos_f32_e32 v68, v69
	v_sin_f32_e32 v74, v69
	v_cos_f32_e32 v69, v72
	v_mul_f32_e32 v94, 0x3e38aa3b, v88
	s_waitcnt vmcnt(7)
	v_pk_mul_f32 v[88:89], v[44:45], v[94:95] op_sel_hi:[1,0]
	s_waitcnt vmcnt(1)
	v_pk_mul_f32 v[122:123], v[20:21], v[94:95] op_sel_hi:[1,0]
	v_pk_mul_f32 v[96:97], v[88:89], v[140:141]
	v_pk_mul_f32 v[88:89], v[46:47], v[94:95] op_sel_hi:[1,0]
	v_pk_mul_f32 v[112:113], v[26:27], v[94:95] op_sel_hi:[1,0]
	v_pk_mul_f32 v[98:99], v[88:89], v[132:133]
	v_pk_mul_f32 v[88:89], v[40:41], v[94:95] op_sel_hi:[1,0]
	v_pk_mul_f32 v[80:81], v[112:113], v[80:81]
	v_pk_mul_f32 v[100:101], v[88:89], v[128:129]
	v_pk_mul_f32 v[88:89], v[42:43], v[94:95] op_sel_hi:[1,0]
	v_pk_mul_f32 v[128:129], v[122:123], v[118:119]
	v_pk_mul_f32 v[102:103], v[88:89], v[120:121]
	v_pk_mul_f32 v[88:89], v[36:37], v[94:95] op_sel_hi:[1,0]
	v_pk_mul_f32 v[118:119], v[22:23], v[94:95] op_sel_hi:[1,0]
	v_pk_mul_f32 v[104:105], v[88:89], v[142:143]
	v_pk_mul_f32 v[88:89], v[38:39], v[94:95] op_sel_hi:[1,0]
	v_sin_f32_e32 v75, v72
	v_pk_mul_f32 v[110:111], v[88:89], v[136:137]
	v_pk_mul_f32 v[88:89], v[32:33], v[94:95] op_sel_hi:[1,0]
	v_mul_f32_e32 v73, v173, v181
	v_pk_mul_f32 v[120:121], v[88:89], v[130:131]
	v_pk_mul_f32 v[88:89], v[34:35], v[94:95] op_sel_hi:[1,0]
	v_pk_mul_f32 v[130:131], v[118:119], v[116:117]
	v_pk_mul_f32 v[124:125], v[88:89], v[124:125]
	v_pk_mul_f32 v[88:89], v[28:29], v[94:95] op_sel_hi:[1,0]
	s_waitcnt vmcnt(0)
	v_pk_mul_f32 v[116:117], v[16:17], v[94:95] op_sel_hi:[1,0]
	v_pk_mul_f32 v[126:127], v[88:89], v[114:115]
	v_pk_mul_f32 v[88:89], v[30:31], v[94:95] op_sel_hi:[1,0]
	v_pk_mul_f32 v[82:83], v[116:117], v[82:83]
	v_pk_mul_f32 v[108:109], v[88:89], v[108:109]
	v_pk_mul_f32 v[88:89], v[24:25], v[94:95] op_sel_hi:[1,0]
	v_pk_mul_f32 v[94:95], v[18:19], v[94:95] op_sel_hi:[1,0]
	v_pk_mul_f32 v[116:117], v[58:59], v[120:121]
	v_pk_mul_f32 v[78:79], v[94:95], v[78:79]
	v_pk_mul_f32 v[94:95], v[48:49], v[104:105]
	v_pk_mul_f32 v[104:105], v[50:51], v[104:105]
	v_pk_fma_f32 v[94:95], v[50:51], v[96:97], v[94:95]
	v_pk_fma_f32 v[96:97], v[48:49], v[96:97], v[104:105] neg_lo:[0,0,1] neg_hi:[0,0,1]
	v_pk_mul_f32 v[104:105], v[52:53], v[110:111]
	v_pk_mul_f32 v[110:111], v[54:55], v[110:111]
	v_pk_fma_f32 v[104:105], v[54:55], v[98:99], v[104:105]
	v_pk_fma_f32 v[98:99], v[52:53], v[98:99], v[110:111] neg_lo:[0,0,1] neg_hi:[0,0,1]
	v_pk_mul_f32 v[110:111], v[56:57], v[120:121]
	v_pk_mul_f32 v[120:121], v[60:61], v[124:125]
	v_pk_fma_f32 v[110:111], v[58:59], v[100:101], v[110:111]
	v_pk_fma_f32 v[100:101], v[56:57], v[100:101], v[116:117] neg_lo:[0,0,1] neg_hi:[0,0,1]
	v_mov_b32_e32 v116, v224
	v_mov_b32_e32 v117, v225
	v_mov_b32_e32 v118, v226
	v_mov_b32_e32 v119, v227
	v_pk_fma_f32 v[132:133], v[62:63], v[102:103], v[120:121]
	v_mov_b32_e32 v120, v228
	v_mov_b32_e32 v121, v229
	v_mov_b32_e32 v122, v230
	v_mov_b32_e32 v123, v231
	v_pk_mul_f32 v[106:107], v[88:89], v[106:107]
	v_mov_b32_e32 v88, v232
	v_mov_b32_e32 v89, v233
	v_mov_b32_e32 v90, v234
	v_mov_b32_e32 v91, v235
	v_mov_b32_e32 v112, v236
	v_mov_b32_e32 v113, v237
	v_mov_b32_e32 v114, v238
	v_mov_b32_e32 v115, v239
	v_pk_mul_f32 v[64:65], v[62:63], v[124:125]
	v_mul_f32_e32 v77, v187, v181
	v_pk_fma_f32 v[64:65], v[60:61], v[102:103], v[64:65] neg_lo:[0,0,1] neg_hi:[0,0,1]
	v_pk_mul_f32 v[102:103], v[66:67], v[128:129]
	v_cos_f32_e32 v72, v73
	v_pk_fma_f32 v[124:125], v[70:71], v[126:127], v[102:103]
	v_pk_mul_f32 v[70:71], v[70:71], v[128:129]
	v_sin_f32_e32 v76, v73
	v_pk_fma_f32 v[66:67], v[66:67], v[126:127], v[70:71] neg_lo:[0,0,1] neg_hi:[0,0,1]
	v_pk_mul_f32 v[70:71], v[68:69], v[130:131]
	v_cos_f32_e32 v73, v77
	v_pk_fma_f32 v[70:71], v[74:75], v[108:109], v[70:71]
	v_pk_mul_f32 v[74:75], v[74:75], v[130:131]
	v_sin_f32_e32 v77, v77
	v_pk_fma_f32 v[68:69], v[68:69], v[108:109], v[74:75] neg_lo:[0,0,1] neg_hi:[0,0,1]
	v_cvt_pk_bf16_f32 v109, v70, v71
	v_mul_f32_e32 v70, v172, v182
	v_mul_f32_e32 v71, v173, v182
	v_mul_f32_e32 v86, v92, v181
	v_mul_f32_e32 v87, v93, v181
	v_cos_f32_e32 v84, v86
	v_sin_f32_e32 v86, v86
	v_cos_f32_e32 v85, v87
	v_sin_f32_e32 v87, v87
	v_pk_mul_f32 v[74:75], v[72:73], v[82:83]
	v_cvt_pk_bf16_f32 v96, v96, v97
	v_cvt_pk_bf16_f32 v97, v98, v99
	v_cvt_pk_bf16_f32 v98, v100, v101
	v_cvt_pk_bf16_f32 v101, v104, v105
	v_cvt_pk_bf16_f32 v104, v66, v67
	v_mul_f32_e32 v66, v170, v182
	v_mul_f32_e32 v67, v171, v182
	v_pk_fma_f32 v[74:75], v[76:77], v[106:107], v[74:75]
	v_pk_mul_f32 v[76:77], v[76:77], v[82:83]
	v_cvt_pk_bf16_f32 v103, v132, v133
	v_pk_fma_f32 v[72:73], v[72:73], v[106:107], v[76:77] neg_lo:[0,0,1] neg_hi:[0,0,1]
	v_pk_mul_f32 v[76:77], v[84:85], v[78:79]
	v_pk_mul_f32 v[78:79], v[86:87], v[78:79]
	v_pk_fma_f32 v[76:77], v[86:87], v[80:81], v[76:77]
	v_pk_fma_f32 v[78:79], v[84:85], v[80:81], v[78:79] neg_lo:[0,0,1] neg_hi:[0,0,1]
	v_cvt_pk_bf16_f32 v100, v94, v95
	v_cvt_pk_bf16_f32 v107, v78, v79
	v_cvt_pk_bf16_f32 v102, v110, v111
	v_cvt_pk_bf16_f32 v111, v76, v77
	v_cvt_pk_bf16_f32 v108, v124, v125
	s_cmp_eq_u32 s0, 0
	s_cselect_b64 s[4:5], -1, 0
	v_cvt_pk_bf16_f32 v99, v64, v65
	v_mul_f32_e32 v65, v165, v182
	v_cndmask_b32_e64 v165, 0, 1, s[4:5]
	s_and_b64 s[4:5], s[4:5], exec
	s_cselect_b32 s3, 0, 0xffffff80
	s_or_b32 s24, s2, s0
	s_add_i32 s4, s3, s24
	v_readlane_b32 s2, v243, 56
	v_readlane_b32 s3, v243, 57
	s_lshl_b32 s6, s1, 7
	s_barrier
	v_cvt_pk_bf16_f32 v105, v68, v69
	v_cos_f32_e32 v64, v65
	v_sin_f32_e32 v68, v65
	v_cos_f32_e32 v65, v66
	v_sin_f32_e32 v69, v66
	v_cvt_pk_bf16_f32 v106, v72, v73
	v_cvt_pk_bf16_f32 v110, v74, v75
	v_cos_f32_e32 v66, v67
	v_sin_f32_e32 v72, v67
	v_cos_f32_e32 v67, v70
	v_sin_f32_e32 v73, v70
	v_mul_f32_e32 v75, v187, v182
	v_cos_f32_e32 v70, v71
	v_sin_f32_e32 v74, v71
	s_waitcnt vmcnt(3)
	v_lshlrev_b32_e32 v194, 16, v116
	v_and_b32_e32 v195, 0xffff0000, v116
	v_lshlrev_b32_e32 v172, 16, v117
	v_and_b32_e32 v173, 0xffff0000, v117
	v_pk_mul_f32 v[116:117], v[194:195], v[194:195]
	v_pk_mul_f32 v[188:189], v[172:173], v[172:173]
	v_add_f32_e32 v116, v116, v117
	v_lshlrev_b32_e32 v142, 16, v118
	v_and_b32_e32 v143, 0xffff0000, v118
	v_add_f32_e32 v116, v188, v116
	v_lshlrev_b32_e32 v134, 16, v119
	v_and_b32_e32 v135, 0xffff0000, v119
	v_pk_mul_f32 v[118:119], v[142:143], v[142:143]
	v_add_f32_e32 v116, v189, v116
	v_add_f32_e32 v116, v118, v116
	v_pk_mul_f32 v[136:137], v[134:135], v[134:135]
	v_add_f32_e32 v116, v119, v116
	s_waitcnt vmcnt(2)
	v_lshlrev_b32_e32 v196, 16, v120
	v_and_b32_e32 v197, 0xffff0000, v120
	v_add_f32_e32 v116, v136, v116
	v_lshlrev_b32_e32 v190, 16, v121
	v_and_b32_e32 v191, 0xffff0000, v121
	v_pk_mul_f32 v[120:121], v[196:197], v[196:197]
	v_add_f32_e32 v116, v137, v116
	v_add_f32_e32 v116, v120, v116
	v_pk_mul_f32 v[192:193], v[190:191], v[190:191]
	v_add_f32_e32 v116, v121, v116
	v_lshlrev_b32_e32 v170, 16, v122
	v_and_b32_e32 v171, 0xffff0000, v122
	v_add_f32_e32 v116, v192, v116
	v_lshlrev_b32_e32 v138, 16, v123
	v_and_b32_e32 v139, 0xffff0000, v123
	v_pk_mul_f32 v[122:123], v[170:171], v[170:171]
	v_add_f32_e32 v116, v193, v116
	v_add_f32_e32 v116, v122, v116
	v_pk_mul_f32 v[140:141], v[138:139], v[138:139]
	v_add_f32_e32 v116, v123, v116
	s_waitcnt vmcnt(1)
	v_lshlrev_b32_e32 v78, 16, v91
	v_and_b32_e32 v79, 0xffff0000, v91
	v_lshlrev_b32_e32 v82, 16, v90
	v_and_b32_e32 v83, 0xffff0000, v90
	v_lshlrev_b32_e32 v90, 16, v88
	v_and_b32_e32 v91, 0xffff0000, v88
	v_add_f32_e32 v116, v140, v116
	v_pk_mul_f32 v[132:133], v[90:91], v[90:91]
	v_add_f32_e32 v116, v141, v116
	v_lshlrev_b32_e32 v86, 16, v89
	v_and_b32_e32 v87, 0xffff0000, v89
	v_add_f32_e32 v116, v132, v116
	v_pk_mul_f32 v[128:129], v[86:87], v[86:87]
	v_add_f32_e32 v116, v133, v116
	v_add_f32_e32 v116, v128, v116
	v_pk_mul_f32 v[126:127], v[82:83], v[82:83]
	v_add_f32_e32 v116, v129, v116
	v_add_f32_e32 v116, v126, v116
	v_pk_mul_f32 v[94:95], v[78:79], v[78:79]
	v_add_f32_e32 v116, v127, v116
	s_waitcnt vmcnt(0)
	v_lshlrev_b32_e32 v88, 16, v112
	v_and_b32_e32 v89, 0xffff0000, v112
	v_add_f32_e32 v94, v94, v116
	v_lshlrev_b32_e32 v84, 16, v113
	v_and_b32_e32 v85, 0xffff0000, v113
	v_pk_mul_f32 v[112:113], v[88:89], v[88:89]
	v_add_f32_e32 v94, v95, v94
	v_add_f32_e32 v94, v112, v94
	v_pk_mul_f32 v[130:131], v[84:85], v[84:85]
	v_add_f32_e32 v94, v113, v94
	v_lshlrev_b32_e32 v80, 16, v114
	v_and_b32_e32 v81, 0xffff0000, v114
	v_add_f32_e32 v94, v130, v94
	v_lshlrev_b32_e32 v76, 16, v115
	v_and_b32_e32 v77, 0xffff0000, v115
	v_pk_mul_f32 v[114:115], v[80:81], v[80:81]
	v_add_f32_e32 v94, v131, v94
	v_add_f32_e32 v94, v114, v94
	v_pk_mul_f32 v[124:125], v[76:77], v[76:77]
	v_add_f32_e32 v94, v115, v94
	v_add_f32_e32 v94, v124, v94
	v_add_f32_e32 v95, v125, v94
	v_mov_b32_e32 v254, v95
	v_mov_b32_e32 v255, v95
	s_nop 1
	v_permlane32_swap_b32_e32 v254, v255
	v_mov_b64_e32 v[120:121], s[2:3]
	v_or_b32_e32 v122, s4, v148
	v_cos_f32_e32 v71, v75
	v_sin_f32_e32 v75, v75
	s_waitcnt lgkmcnt(0)
	v_add_f32_e32 v95, v254, v255
	v_fmamk_f32 v95, v95, 0x3c800000, v186
	v_rsq_f32_e32 v112, v95
	v_mul_f32_e32 v94, v92, v182
	v_mul_f32_e32 v95, v93, v182
	v_cos_f32_e32 v92, v94
	v_mul_f32_e32 v128, 0x3e38aa3b, v112
	v_add_u32_e32 v112, s4, v177
	v_mad_i64_i32 v[112:113], s[2:3], v112, s10, v[120:121]
	v_mad_i64_i32 v[120:121], s[2:3], v122, s10, v[120:121]
	v_lshl_add_u64 v[112:113], v[112:113], 0, s[6:7]
	v_lshl_add_u64 v[120:121], v[120:121], 0, s[6:7]
	v_lshl_add_u64 v[116:117], v[112:113], 0, v[144:145]
	v_lshl_add_u64 v[124:125], v[112:113], 0, v[144:145]
	s_nop 0
	s_nop 0
	s_nop 0
	v_pk_mul_f32 v[36:37], v[36:37], v[128:129] op_sel_hi:[1,0]
	s_nop 0
	v_pk_mul_f32 v[44:45], v[44:45], v[128:129] op_sel_hi:[1,0]
	s_nop 0
	v_pk_mul_f32 v[36:37], v[36:37], v[196:197]
	v_pk_mul_f32 v[38:39], v[38:39], v[128:129] op_sel_hi:[1,0]
	v_pk_mul_f32 v[18:19], v[18:19], v[128:129] op_sel_hi:[1,0]
	v_pk_mul_f32 v[44:45], v[44:45], v[194:195]
	v_pk_mul_f32 v[46:47], v[46:47], v[128:129] op_sel_hi:[1,0]
	v_pk_mul_f32 v[38:39], v[38:39], v[190:191]
	v_pk_mul_f32 v[32:33], v[32:33], v[128:129] op_sel_hi:[1,0]
	v_pk_mul_f32 v[18:19], v[18:19], v[76:77]
	v_pk_mul_f32 v[76:77], v[48:49], v[36:37]
	v_pk_mul_f32 v[36:37], v[50:51], v[36:37]
	v_pk_mul_f32 v[46:47], v[46:47], v[172:173]
	v_pk_mul_f32 v[40:41], v[40:41], v[128:129] op_sel_hi:[1,0]
	v_pk_mul_f32 v[32:33], v[32:33], v[170:171]
	v_pk_mul_f32 v[34:35], v[34:35], v[128:129] op_sel_hi:[1,0]
	v_pk_fma_f32 v[76:77], v[50:51], v[44:45], v[76:77]
	v_pk_fma_f32 v[36:37], v[48:49], v[44:45], v[36:37] neg_lo:[0,0,1] neg_hi:[0,0,1]
	v_pk_mul_f32 v[44:45], v[52:53], v[38:39]
	v_pk_mul_f32 v[38:39], v[54:55], v[38:39]
	v_pk_mul_f32 v[40:41], v[40:41], v[142:143]
	v_pk_mul_f32 v[42:43], v[42:43], v[128:129] op_sel_hi:[1,0]
	v_pk_mul_f32 v[34:35], v[34:35], v[138:139]
	v_pk_mul_f32 v[20:21], v[20:21], v[128:129] op_sel_hi:[1,0]
	v_pk_fma_f32 v[44:45], v[54:55], v[46:47], v[44:45]
	v_pk_fma_f32 v[38:39], v[52:53], v[46:47], v[38:39] neg_lo:[0,0,1] neg_hi:[0,0,1]
	v_pk_mul_f32 v[46:47], v[56:57], v[32:33]
	v_pk_mul_f32 v[32:33], v[58:59], v[32:33]
	v_sin_f32_e32 v94, v94
	v_cos_f32_e32 v93, v95
	v_sin_f32_e32 v95, v95
	v_pk_mul_f32 v[42:43], v[42:43], v[134:135]
	v_pk_mul_f32 v[28:29], v[28:29], v[128:129] op_sel_hi:[1,0]
	v_pk_mul_f32 v[20:21], v[20:21], v[88:89]
	v_pk_mul_f32 v[22:23], v[22:23], v[128:129] op_sel_hi:[1,0]
	v_pk_fma_f32 v[46:47], v[58:59], v[40:41], v[46:47]
	v_pk_fma_f32 v[32:33], v[56:57], v[40:41], v[32:33] neg_lo:[0,0,1] neg_hi:[0,0,1]
	v_pk_mul_f32 v[40:41], v[60:61], v[34:35]
	v_pk_mul_f32 v[34:35], v[62:63], v[34:35]
	v_pk_mul_f32 v[28:29], v[28:29], v[90:91]
	v_pk_mul_f32 v[30:31], v[30:31], v[128:129] op_sel_hi:[1,0]
	v_pk_mul_f32 v[22:23], v[22:23], v[84:85]
	v_pk_mul_f32 v[16:17], v[16:17], v[128:129] op_sel_hi:[1,0]
	v_pk_fma_f32 v[40:41], v[62:63], v[42:43], v[40:41]
	v_pk_fma_f32 v[34:35], v[60:61], v[42:43], v[34:35] neg_lo:[0,0,1] neg_hi:[0,0,1]
	v_pk_mul_f32 v[42:43], v[64:65], v[20:21]
	v_pk_mul_f32 v[20:21], v[68:69], v[20:21]
	v_pk_mul_f32 v[30:31], v[30:31], v[86:87]
	v_pk_mul_f32 v[24:25], v[24:25], v[128:129] op_sel_hi:[1,0]
	v_pk_mul_f32 v[16:17], v[16:17], v[80:81]
	v_pk_fma_f32 v[42:43], v[68:69], v[28:29], v[42:43]
	v_pk_fma_f32 v[20:21], v[64:65], v[28:29], v[20:21] neg_lo:[0,0,1] neg_hi:[0,0,1]
	v_pk_mul_f32 v[28:29], v[66:67], v[22:23]
	v_pk_mul_f32 v[22:23], v[72:73], v[22:23]
	v_pk_mul_f32 v[24:25], v[24:25], v[82:83]
	v_pk_mul_f32 v[26:27], v[26:27], v[128:129] op_sel_hi:[1,0]
	v_pk_fma_f32 v[28:29], v[72:73], v[30:31], v[28:29]
	v_pk_fma_f32 v[22:23], v[66:67], v[30:31], v[22:23] neg_lo:[0,0,1] neg_hi:[0,0,1]
	v_pk_mul_f32 v[30:31], v[70:71], v[16:17]
	v_pk_mul_f32 v[16:17], v[74:75], v[16:17]
	v_pk_mul_f32 v[26:27], v[26:27], v[78:79]
	v_pk_fma_f32 v[30:31], v[74:75], v[24:25], v[30:31]
	v_pk_fma_f32 v[16:17], v[70:71], v[24:25], v[16:17] neg_lo:[0,0,1] neg_hi:[0,0,1]
	v_pk_mul_f32 v[24:25], v[92:93], v[18:19]
	v_pk_mul_f32 v[18:19], v[94:95], v[18:19]
	v_pk_fma_f32 v[24:25], v[94:95], v[26:27], v[24:25]
	v_pk_fma_f32 v[18:19], v[92:93], v[26:27], v[18:19] neg_lo:[0,0,1] neg_hi:[0,0,1]
	v_cvt_pk_bf16_f32 v142, v30, v31
	s_cmpk_eq_i32 s0, 0x1f80
	v_mov_b32_e32 v30, v145
	v_mov_b32_e32 v31, v145
	v_cvt_pk_bf16_f32 v128, v36, v37
	v_cvt_pk_bf16_f32 v129, v38, v39
	v_cvt_pk_bf16_f32 v130, v32, v33
	v_cvt_pk_bf16_f32 v131, v34, v35
	v_cvt_pk_bf16_f32 v132, v76, v77
	v_cvt_pk_bf16_f32 v133, v44, v45
	v_cvt_pk_bf16_f32 v134, v46, v47
	v_cvt_pk_bf16_f32 v135, v40, v41
	v_cvt_pk_bf16_f32 v136, v20, v21
	v_cvt_pk_bf16_f32 v137, v22, v23
	v_cvt_pk_bf16_f32 v138, v16, v17
	v_cvt_pk_bf16_f32 v139, v18, v19
	v_cvt_pk_bf16_f32 v140, v42, v43
	v_cvt_pk_bf16_f32 v141, v28, v29
	v_cvt_pk_bf16_f32 v143, v24, v25
	s_cselect_b32 s22, 3, 2
	v_writelane_b32 v243, s11, 60
	s_and_b32 s23, s11, 0xffffff00
	s_mov_b32 s1, s7
	v_mov_b32_e32 v16, v145
	v_mov_b32_e32 v17, v145
	v_mov_b32_e32 v18, v145
	v_mov_b32_e32 v19, v145
	v_mov_b32_e32 v20, v145
	v_mov_b32_e32 v21, v145
	v_mov_b32_e32 v22, v145
	v_mov_b32_e32 v23, v145
	v_mov_b32_e32 v24, v145
	v_mov_b32_e32 v25, v145
	v_mov_b32_e32 v26, v145
	v_mov_b32_e32 v27, v145
	v_mov_b32_e32 v28, v145
	v_mov_b32_e32 v29, v145
	v_mov_b64_e32 v[46:47], v[30:31]
	v_mov_b64_e32 v[62:63], v[30:31]
	v_mov_b64_e32 v[78:79], v[30:31]
	v_ashrrev_i32_e32 v161, 31, v160
	v_ashrrev_i32_e32 v167, 31, v166
	s_mov_b32 s33, 0
	v_readfirstlane_b32 s25, v165
	s_add_i32 s23, s23, 0xfe80
	s_addk_i32 s24, 0xff80
	v_lshl_add_u64 v[170:171], v[156:157], 0, s[6:7]
	v_writelane_b32 v243, s0, 50
	v_lshl_add_u64 v[172:173], v[158:159], 0, s[6:7]
	v_mov_b64_e32 v[44:45], v[28:29]
	v_mov_b64_e32 v[42:43], v[26:27]
	v_mov_b64_e32 v[40:41], v[24:25]
	v_mov_b64_e32 v[38:39], v[22:23]
	v_mov_b64_e32 v[36:37], v[20:21]
	v_mov_b64_e32 v[34:35], v[18:19]
	v_mov_b64_e32 v[32:33], v[16:17]
	v_mov_b64_e32 v[60:61], v[28:29]
	v_mov_b64_e32 v[58:59], v[26:27]
	v_mov_b64_e32 v[56:57], v[24:25]
	v_mov_b64_e32 v[54:55], v[22:23]
	v_mov_b64_e32 v[52:53], v[20:21]
	v_mov_b64_e32 v[50:51], v[18:19]
	v_mov_b64_e32 v[48:49], v[16:17]
	v_mov_b64_e32 v[76:77], v[28:29]
	v_mov_b64_e32 v[74:75], v[26:27]
	v_mov_b64_e32 v[72:73], v[24:25]
	v_mov_b64_e32 v[70:71], v[22:23]
	v_mov_b64_e32 v[68:69], v[20:21]
	v_mov_b64_e32 v[66:67], v[18:19]
	v_mov_b64_e32 v[64:65], v[16:17]
	v_mov_b32_e32 v187, 0
	v_mov_b32_e32 v188, 0
	s_waitcnt vmcnt(2)
	ds_write_b128 v179, v[208:211]
	ds_write_b128 v179, v[204:207] offset:16
	s_waitcnt vmcnt(1)
	ds_write_b16 v153, v212 offset:18432
	ds_write_b16_d16_hi v153, v212 offset:18696
	ds_write_b16 v153, v213 offset:18960
	ds_write_b16_d16_hi v153, v213 offset:19224
	ds_write_b16 v153, v214 offset:19488
	ds_write_b16_d16_hi v153, v214 offset:19752
	ds_write_b16 v153, v215 offset:20016
	ds_write_b16_d16_hi v153, v215 offset:20280
	s_waitcnt vmcnt(0)
	ds_write_b16 v153, v216 offset:20544
	ds_write_b16_d16_hi v153, v216 offset:20808
	ds_write_b16 v153, v217 offset:21072
	ds_write_b16_d16_hi v153, v217 offset:21336
	ds_write_b16 v153, v218 offset:21600
	ds_write_b16_d16_hi v153, v218 offset:21864
	ds_write_b16 v153, v219 offset:22128
	ds_write_b16_d16_hi v153, v219 offset:22392
	s_waitcnt lgkmcnt(0)
	s_barrier
	v_writelane_b32 v243, s1, 51
